# pace the weight-conversion workgroups during the layer-0 recurrence (s_sleep per item)
# baseline (speedup 1.0000x reference)
; #define LAS __attribute__((address_space(3)))
; __device__ __forceinline__ unsigned pk2(float lo, float hi) { f32x2_t v = {lo, hi}; bf16x2_t b = __builtin_convertvector(v, bf16x2_t); return __builtin_bit_cast(unsigned, b); }
; __device__ __forceinline__ void transpose_item(const float* W, int K, int N, bf16* WT, const float* scale, LAS float* scr, int item, int lane) {
;     const int nblk = N / 32, kb = item / nblk, nb = item % nblk, k0 = 64 * kb, n0 = 32 * nb;
;     {
;         const int q = lane & 7, r = lane >> 3;
;         f32x4 v[8];
; #pragma unroll
;         for (int i = 0; i < 8; ++i) v[i] = *(const f32x4*)(W + (size_t)(k0 + 8 * i + r) * N + n0 + 4 * q);
; #pragma unroll
;         for (int i = 0; i < 8; ++i) { const int kk = 8 * i + r; f32x4 x = v[i]; if (scale) x = x * scale[k0 + kk];
;             scr[kk * 33 + 4 * q + 0] = x[0]; scr[kk * 33 + 4 * q + 1] = x[1]; scr[kk * 33 + 4 * q + 2] = x[2]; scr[kk * 33 + 4 * q + 3] = x[3]; }
;     }
;     asm volatile("s_waitcnt lgkmcnt(0)" ::: "memory");
;     const int c = lane & 7;
; #pragma unroll
;     for (int j = 0; j < 4; ++j) { const int n = (lane >> 3) + 8 * j; const LAS float* s = scr + (8 * c) * 33 + n;
;         v4u o; o.x = pk2(s[0 * 33], s[1 * 33]); o.y = pk2(s[2 * 33], s[3 * 33]); o.z = pk2(s[4 * 33], s[5 * 33]); o.w = pk2(s[6 * 33], s[7 * 33]);
;         *(v4u*)(WT + (size_t)(n0 + n) * K + k0 + 8 * c) = o; }
; __device__ __forceinline__ void convert_weight(const float* W, int K, int N, bf16* WT, const float* scale, LAS unsigned char* lds, int gw, int ngw) {
;     ...
;     for (int it = gw; it < nitems; it += ngw) transpose_item(W, K, N, WT, scale, scr, it, lane);
.LBB0_1263:
	s_sleep 64
	s_mul_hi_i32 s0, s6, 0x66666667
	s_lshr_b32 s1, s0, 31
	s_ashr_i32 s0, s0, 7
	s_add_i32 s0, s0, s1
	s_lshl_b32 s2, s0, 6
	s_mulk_i32 s0, 0xd800
	s_add_i32 s0, s4, s0
	s_ashr_i32 s1, s0, 31
	s_waitcnt vmcnt(1)
	v_or_b32_e32 v48, s2, v1
	v_lshl_add_u64 v[2:3], s[0:1], 2, v[22:23]
	v_mad_i64_i32 v[4:5], s[8:9], v48, s12, v[2:3]
	global_load_dwordx4 v[36:39], v[4:5], off nt
	v_or_b32_e32 v4, 8, v48
	v_mad_i64_i32 v[4:5], s[8:9], v4, s12, v[2:3]
	global_load_dwordx4 v[40:43], v[4:5], off nt
	v_or_b32_e32 v4, 16, v48
	v_mad_i64_i32 v[4:5], s[8:9], v4, s12, v[2:3]
	global_load_dwordx4 v[44:47], v[4:5], off nt
	v_or_b32_e32 v4, 24, v48
	v_mad_i64_i32 v[4:5], s[8:9], v4, s12, v[2:3]
	global_load_dwordx4 v[18:21], v[4:5], off nt
	v_or_b32_e32 v4, 32, v48
	v_mad_i64_i32 v[4:5], s[8:9], v4, s12, v[2:3]
	global_load_dwordx4 v[14:17], v[4:5], off nt
	v_or_b32_e32 v4, 40, v48
	v_mad_i64_i32 v[4:5], s[8:9], v4, s12, v[2:3]
	global_load_dwordx4 v[10:13], v[4:5], off nt
	v_or_b32_e32 v4, 48, v48
	v_ashrrev_i32_e32 v49, 31, v48
	v_mad_i64_i32 v[4:5], s[8:9], v4, s12, v[2:3]
	global_load_dwordx4 v[6:9], v[4:5], off nt
	v_or_b32_e32 v4, 56, v48
	v_lshl_add_u64 v[48:49], v[48:49], 2, s[10:11]
	global_load_dword v48, v[48:49], off
	v_mad_i64_i32 v[2:3], s[8:9], v4, s12, v[2:3]
	global_load_dwordx4 v[2:5], v[2:3], off nt
	v_add_u32_e32 v35, 0x420, v34
	s_ashr_i32 s3, s2, 31
	s_add_i32 s6, s6, s7
	s_add_i32 s4, s4, s5
	s_cmpk_lt_i32 s6, 0x1400
	s_waitcnt vmcnt(1)
	v_pk_mul_f32 v[36:37], v[36:37], v[48:49] op_sel_hi:[1,0]
	v_pk_mul_f32 v[38:39], v[38:39], v[48:49] op_sel_hi:[1,0]
	ds_write2_b32 v34, v36, v37 offset1:1
	ds_write2_b32 v34, v38, v39 offset0:2 offset1:3
	v_or_b32_e32 v36, s2, v26
	v_ashrrev_i32_e32 v37, 31, v36
	v_lshl_add_u64 v[36:37], v[36:37], 2, s[10:11]
	global_load_dword v36, v[36:37], off
	s_waitcnt vmcnt(0)
	v_pk_mul_f32 v[38:39], v[42:43], v[36:37] op_sel_hi:[1,0]
	v_pk_mul_f32 v[36:37], v[40:41], v[36:37] op_sel_hi:[1,0]
	ds_write2_b32 v35, v36, v37 offset1:1
	v_or_b32_e32 v36, s2, v27
	v_ashrrev_i32_e32 v37, 31, v36
	v_lshl_add_u64 v[36:37], v[36:37], 2, s[10:11]
	global_load_dword v36, v[36:37], off
	v_add_u32_e32 v35, 0x428, v34
	ds_write2_b32 v35, v38, v39 offset1:1
	v_add_u32_e32 v35, 0x840, v34
	s_waitcnt vmcnt(0)
	v_pk_mul_f32 v[38:39], v[46:47], v[36:37] op_sel_hi:[1,0]
	v_pk_mul_f32 v[36:37], v[44:45], v[36:37] op_sel_hi:[1,0]
	ds_write2_b32 v35, v36, v37 offset1:1
	v_or_b32_e32 v36, s2, v28
	v_ashrrev_i32_e32 v37, 31, v36
	v_lshl_add_u64 v[36:37], v[36:37], 2, s[10:11]
	global_load_dword v36, v[36:37], off
	v_add_u32_e32 v35, 0x848, v34
	ds_write2_b32 v35, v38, v39 offset1:1
	v_add_u32_e32 v35, 0xc60, v34
	v_add_u32_e32 v38, s0, v1
	v_ashrrev_i32_e32 v39, 31, v38
	v_lshlrev_b64 v[40:41], 11, v[38:39]
	s_waitcnt vmcnt(0)
	v_pk_mul_f32 v[18:19], v[18:19], v[36:37] op_sel_hi:[1,0]
	v_pk_mul_f32 v[20:21], v[20:21], v[36:37] op_sel_hi:[1,0]
	ds_write2_b32 v35, v18, v19 offset1:1
	v_add_u32_e32 v18, 0xc68, v34
	ds_write2_b32 v18, v20, v21 offset1:1
	v_or_b32_e32 v18, s2, v29
	v_ashrrev_i32_e32 v19, 31, v18
	v_lshl_add_u64 v[18:19], v[18:19], 2, s[10:11]
	global_load_dword v18, v[18:19], off
	s_waitcnt vmcnt(0)
	v_pk_mul_f32 v[16:17], v[16:17], v[18:19] op_sel_hi:[1,0]
	v_pk_mul_f32 v[14:15], v[14:15], v[18:19] op_sel_hi:[1,0]
	v_add_u32_e32 v18, 0x1080, v34
	ds_write2_b32 v18, v14, v15 offset1:1
	v_add_u32_e32 v14, 0x1088, v34
	ds_write2_b32 v14, v16, v17 offset1:1
	v_or_b32_e32 v14, s2, v30
	v_ashrrev_i32_e32 v15, 31, v14
	v_lshl_add_u64 v[14:15], v[14:15], 2, s[10:11]
	global_load_dword v14, v[14:15], off
	s_waitcnt vmcnt(0)
	v_pk_mul_f32 v[12:13], v[12:13], v[14:15] op_sel_hi:[1,0]
	v_pk_mul_f32 v[10:11], v[10:11], v[14:15] op_sel_hi:[1,0]
	v_add_u32_e32 v14, 0x14a0, v34
	ds_write2_b32 v14, v10, v11 offset1:1
	v_add_u32_e32 v10, 0x14a8, v34
	ds_write2_b32 v10, v12, v13 offset1:1
	v_or_b32_e32 v10, s2, v31
	v_ashrrev_i32_e32 v11, 31, v10
	v_lshl_add_u64 v[10:11], v[10:11], 2, s[10:11]
	global_load_dword v10, v[10:11], off
	s_waitcnt vmcnt(0)
	v_pk_mul_f32 v[8:9], v[8:9], v[10:11] op_sel_hi:[1,0]
	v_pk_mul_f32 v[6:7], v[6:7], v[10:11] op_sel_hi:[1,0]
	v_add_u32_e32 v10, 0x18c0, v34
	ds_write2_b32 v10, v6, v7 offset1:1
	v_add_u32_e32 v6, 0x18c8, v34
	ds_write2_b32 v6, v8, v9 offset1:1
	v_or_b32_e32 v6, s2, v32
	v_ashrrev_i32_e32 v7, 31, v6
	v_lshl_add_u64 v[6:7], v[6:7], 2, s[10:11]
	global_load_dword v6, v[6:7], off
	s_waitcnt vmcnt(0)
	v_pk_mul_f32 v[4:5], v[4:5], v[6:7] op_sel_hi:[1,0]
	v_pk_mul_f32 v[2:3], v[2:3], v[6:7] op_sel_hi:[1,0]
	v_add_u32_e32 v6, 0x1ce0, v34
	ds_write2_b32 v6, v2, v3 offset1:1
	v_add_u32_e32 v2, 0x1ce8, v34
	ds_write2_b32 v2, v4, v5 offset1:1
	s_waitcnt lgkmcnt(0)
	ds_read2_b32 v[8:9], v33 offset0:33 offset1:41
	ds_read2_b32 v[10:11], v33 offset1:8
	ds_read2_b32 v[12:13], v33 offset0:66 offset1:74
	ds_read2_b32 v[14:15], v33 offset0:99 offset1:107
	ds_read2_b32 v[16:17], v33 offset0:132 offset1:140
	ds_read2_b32 v[18:19], v33 offset0:165 offset1:173
	ds_read2_b32 v[20:21], v33 offset0:198 offset1:206
	ds_read2_b32 v[36:37], v33 offset0:231 offset1:239
	v_lshl_add_u64 v[6:7], s[2:3], 1, v[24:25]
	s_waitcnt lgkmcnt(6)
	v_cvt_pk_bf16_f32 v2, v10, v8
	s_waitcnt lgkmcnt(4)
	v_cvt_pk_bf16_f32 v3, v12, v14
	s_waitcnt lgkmcnt(2)
	v_cvt_pk_bf16_f32 v4, v16, v18
	s_waitcnt lgkmcnt(0)
	v_cvt_pk_bf16_f32 v5, v20, v36
	v_lshl_add_u64 v[40:41], v[6:7], 0, v[40:41]
	v_add_u32_e32 v8, 8, v38
	global_store_dwordx4 v[40:41], v[2:5], off nt
	v_add_u32_e32 v40, 16, v38
	v_ashrrev_i32_e32 v41, 31, v40
	v_cvt_pk_bf16_f32 v2, v11, v9
	v_ashrrev_i32_e32 v9, 31, v8
	v_lshlrev_b64 v[8:9], 11, v[8:9]
	v_cvt_pk_bf16_f32 v3, v13, v15
	v_cvt_pk_bf16_f32 v4, v17, v19
	v_cvt_pk_bf16_f32 v5, v21, v37
	v_lshl_add_u64 v[8:9], v[6:7], 0, v[8:9]
	global_store_dwordx4 v[8:9], v[2:5], off nt
	ds_read2_b32 v[8:9], v33 offset0:49 offset1:57
	ds_read2_b32 v[10:11], v33 offset0:16 offset1:24
	ds_read2_b32 v[12:13], v33 offset0:82 offset1:90
	ds_read2_b32 v[14:15], v33 offset0:115 offset1:123
	ds_read2_b32 v[16:17], v33 offset0:148 offset1:156
	ds_read2_b32 v[18:19], v33 offset0:181 offset1:189
	ds_read2_b32 v[20:21], v33 offset0:214 offset1:222
	ds_read2_b32 v[36:37], v33 offset0:247 offset1:255
	v_lshlrev_b64 v[40:41], 11, v[40:41]
	s_waitcnt lgkmcnt(6)
	v_cvt_pk_bf16_f32 v2, v10, v8
	s_waitcnt lgkmcnt(4)
	v_cvt_pk_bf16_f32 v3, v12, v14
	s_waitcnt lgkmcnt(2)
	v_cvt_pk_bf16_f32 v4, v16, v18
	s_waitcnt lgkmcnt(0)
	v_cvt_pk_bf16_f32 v5, v20, v36
	v_lshl_add_u64 v[40:41], v[6:7], 0, v[40:41]
	v_add_u32_e32 v8, 24, v38
	global_store_dwordx4 v[40:41], v[2:5], off nt
	s_nop 1
	v_cvt_pk_bf16_f32 v2, v11, v9
	v_ashrrev_i32_e32 v9, 31, v8
	v_lshlrev_b64 v[8:9], 11, v[8:9]
	v_cvt_pk_bf16_f32 v3, v13, v15
	v_cvt_pk_bf16_f32 v4, v17, v19
	v_cvt_pk_bf16_f32 v5, v21, v37
	v_lshl_add_u64 v[6:7], v[6:7], 0, v[8:9]
	global_store_dwordx4 v[6:7], v[2:5], off nt
	s_waitcnt lgkmcnt(0)
	s_cbranch_scc1 .LBB0_1263

; #define LAS __attribute__((address_space(3)))
; __device__ __forceinline__ unsigned pk2(float lo, float hi) { f32x2_t v = {lo, hi}; bf16x2_t b = __builtin_convertvector(v, bf16x2_t); return __builtin_bit_cast(unsigned, b); }
; __device__ __forceinline__ void transpose_item(const float* W, int K, int N, bf16* WT, const float* scale, LAS float* scr, int item, int lane) {
;     const int nblk = N / 32, kb = item / nblk, nb = item % nblk, k0 = 64 * kb, n0 = 32 * nb;
;     {
;         const int q = lane & 7, r = lane >> 3;
;         f32x4 v[8];
; #pragma unroll
;         for (int i = 0; i < 8; ++i) v[i] = *(const f32x4*)(W + (size_t)(k0 + 8 * i + r) * N + n0 + 4 * q);
; #pragma unroll
;         for (int i = 0; i < 8; ++i) { const int kk = 8 * i + r; f32x4 x = v[i]; if (scale) x = x * scale[k0 + kk];
;             scr[kk * 33 + 4 * q + 0] = x[0]; scr[kk * 33 + 4 * q + 1] = x[1]; scr[kk * 33 + 4 * q + 2] = x[2]; scr[kk * 33 + 4 * q + 3] = x[3]; }
;     }
;     asm volatile("s_waitcnt lgkmcnt(0)" ::: "memory");
;     const int c = lane & 7;
; #pragma unroll
;     for (int j = 0; j < 4; ++j) { const int n = (lane >> 3) + 8 * j; const LAS float* s = scr + (8 * c) * 33 + n;
;         v4u o; o.x = pk2(s[0 * 33], s[1 * 33]); o.y = pk2(s[2 * 33], s[3 * 33]); o.z = pk2(s[4 * 33], s[5 * 33]); o.w = pk2(s[6 * 33], s[7 * 33]);
;         *(v4u*)(WT + (size_t)(n0 + n) * K + k0 + 8 * c) = o; }
; __device__ __forceinline__ void convert_weight(const float* W, int K, int N, bf16* WT, const float* scale, LAS unsigned char* lds, int gw, int ngw) {
;     ...
;     for (int it = gw; it < nitems; it += ngw) transpose_item(W, K, N, WT, scale, scr, it, lane);
.LBB0_1266:
	s_sleep 64
	s_ashr_i32 s2, s8, 31
	s_lshr_b32 s2, s2, 27
	s_add_i32 s2, s8, s2
	s_ashr_i32 s2, s2, 5
	s_lshl_b32 s4, s2, 6
	s_lshl_b32 s2, s2, 10
	s_sub_i32 s2, s6, s2
	s_waitcnt vmcnt(24)
	v_or_b32_e32 v38, s4, v1
	s_ashr_i32 s3, s2, 31
	s_waitcnt vmcnt(22)
	v_ashrrev_i32_e32 v39, 31, v38
	v_or_b32_e32 v6, 8, v38
	v_lshl_add_u64 v[18:19], s[2:3], 2, v[14:15]
	v_lshlrev_b64 v[2:3], 12, v[38:39]
	v_ashrrev_i32_e32 v7, 31, v6
	v_lshl_add_u64 v[2:3], v[18:19], 0, v[2:3]
	v_lshlrev_b64 v[6:7], 12, v[6:7]
	v_or_b32_e32 v10, 16, v38
	global_load_dwordx4 v[2:5], v[2:3], off nt
	v_lshl_add_u64 v[6:7], v[18:19], 0, v[6:7]
	v_ashrrev_i32_e32 v11, 31, v10
	global_load_dwordx4 v[6:9], v[6:7], off nt
	v_lshlrev_b64 v[10:11], 12, v[10:11]
	v_or_b32_e32 v22, 24, v38
	v_lshl_add_u64 v[10:11], v[18:19], 0, v[10:11]
	v_ashrrev_i32_e32 v23, 31, v22
	global_load_dwordx4 v[10:13], v[10:11], off nt
	v_lshlrev_b64 v[22:23], 12, v[22:23]
	v_or_b32_e32 v26, 32, v38
	v_lshl_add_u64 v[22:23], v[18:19], 0, v[22:23]
	v_ashrrev_i32_e32 v27, 31, v26
	global_load_dwordx4 v[22:25], v[22:23], off nt
	v_lshlrev_b64 v[26:27], 12, v[26:27]
	v_or_b32_e32 v30, 40, v38
	v_lshl_add_u64 v[26:27], v[18:19], 0, v[26:27]
	v_ashrrev_i32_e32 v31, 31, v30
	global_load_dwordx4 v[26:29], v[26:27], off nt
	v_lshlrev_b64 v[30:31], 12, v[30:31]
	v_or_b32_e32 v34, 48, v38
	v_lshl_add_u64 v[30:31], v[18:19], 0, v[30:31]
	v_ashrrev_i32_e32 v35, 31, v34
	global_load_dwordx4 v[30:33], v[30:31], off nt
	v_lshlrev_b64 v[34:35], 12, v[34:35]
	v_or_b32_e32 v38, 56, v38
	v_lshl_add_u64 v[34:35], v[18:19], 0, v[34:35]
	v_ashrrev_i32_e32 v39, 31, v38
	global_load_dwordx4 v[34:37], v[34:35], off nt
	v_lshlrev_b64 v[38:39], 12, v[38:39]
	v_lshl_add_u64 v[18:19], v[18:19], 0, v[38:39]
	global_load_dwordx4 v[38:41], v[18:19], off nt
	s_ashr_i32 s5, s4, 31
	s_add_i32 s8, s8, s9
	s_add_i32 s6, s6, s7
	s_cmpk_lt_i32 s8, 0x200
	s_waitcnt vmcnt(7)
	ds_write2_b32 v21, v2, v3 offset1:1
	ds_write2_b32 v21, v4, v5 offset0:2 offset1:3
	v_add_u32_e32 v2, 0x420, v21
	s_waitcnt vmcnt(6)
	ds_write2_b32 v2, v6, v7 offset1:1
	v_add_u32_e32 v2, 0x428, v21
	ds_write2_b32 v2, v8, v9 offset1:1
	v_add_u32_e32 v2, 0x840, v21
	v_lshl_add_u64 v[6:7], s[4:5], 1, v[16:17]
	s_waitcnt vmcnt(5)
	ds_write2_b32 v2, v10, v11 offset1:1
	v_add_u32_e32 v2, 0x848, v21
	ds_write2_b32 v2, v12, v13 offset1:1
	v_add_u32_e32 v2, 0xc60, v21
	s_waitcnt vmcnt(4)
	ds_write2_b32 v2, v22, v23 offset1:1
	v_add_u32_e32 v2, 0xc68, v21
	ds_write2_b32 v2, v24, v25 offset1:1
	v_add_u32_e32 v2, 0x1080, v21
	s_waitcnt vmcnt(3)
	ds_write2_b32 v2, v26, v27 offset1:1
	v_add_u32_e32 v2, 0x1088, v21
	ds_write2_b32 v2, v28, v29 offset1:1
	v_add_u32_e32 v2, 0x14a0, v21
	s_waitcnt vmcnt(2)
	ds_write2_b32 v2, v30, v31 offset1:1
	v_add_u32_e32 v2, 0x14a8, v21
	ds_write2_b32 v2, v32, v33 offset1:1
	v_add_u32_e32 v2, 0x18c0, v21
	v_add_u32_e32 v30, s2, v1
	s_waitcnt vmcnt(1)
	ds_write2_b32 v2, v34, v35 offset1:1
	v_add_u32_e32 v2, 0x18c8, v21
	ds_write2_b32 v2, v36, v37 offset1:1
	v_add_u32_e32 v2, 0x1ce0, v21
	s_waitcnt vmcnt(0)
	ds_write2_b32 v2, v38, v39 offset1:1
	v_add_u32_e32 v2, 0x1ce8, v21
	ds_write2_b32 v2, v40, v41 offset1:1
	s_waitcnt lgkmcnt(0)
	ds_read2_b32 v[8:9], v20 offset0:33 offset1:41
	ds_read2_b32 v[10:11], v20 offset1:8
	ds_read2_b32 v[12:13], v20 offset0:66 offset1:74
	ds_read2_b32 v[18:19], v20 offset0:99 offset1:107
	ds_read2_b32 v[22:23], v20 offset0:132 offset1:140
	ds_read2_b32 v[24:25], v20 offset0:165 offset1:173
	ds_read2_b32 v[26:27], v20 offset0:198 offset1:206
	ds_read2_b32 v[28:29], v20 offset0:231 offset1:239
	v_ashrrev_i32_e32 v31, 31, v30
	v_lshlrev_b64 v[32:33], 11, v[30:31]
	s_waitcnt lgkmcnt(6)
	v_cvt_pk_bf16_f32 v2, v10, v8
	s_waitcnt lgkmcnt(4)
	v_cvt_pk_bf16_f32 v3, v12, v18
	s_waitcnt lgkmcnt(2)
	v_cvt_pk_bf16_f32 v4, v22, v24
	s_waitcnt lgkmcnt(0)
	v_cvt_pk_bf16_f32 v5, v26, v28
	v_lshl_add_u64 v[32:33], v[6:7], 0, v[32:33]
	v_add_u32_e32 v8, 8, v30
	global_store_dwordx4 v[32:33], v[2:5], off nt
	v_add_u32_e32 v32, 16, v30
	v_ashrrev_i32_e32 v33, 31, v32
	v_cvt_pk_bf16_f32 v2, v11, v9
	v_ashrrev_i32_e32 v9, 31, v8
	v_lshlrev_b64 v[8:9], 11, v[8:9]
	v_cvt_pk_bf16_f32 v3, v13, v19
	v_cvt_pk_bf16_f32 v4, v23, v25
	v_cvt_pk_bf16_f32 v5, v27, v29
	v_lshl_add_u64 v[8:9], v[6:7], 0, v[8:9]
	global_store_dwordx4 v[8:9], v[2:5], off nt
	ds_read2_b32 v[8:9], v20 offset0:49 offset1:57
	ds_read2_b32 v[10:11], v20 offset0:16 offset1:24
	ds_read2_b32 v[12:13], v20 offset0:82 offset1:90
	ds_read2_b32 v[18:19], v20 offset0:115 offset1:123
	ds_read2_b32 v[22:23], v20 offset0:148 offset1:156
	ds_read2_b32 v[24:25], v20 offset0:181 offset1:189
	ds_read2_b32 v[26:27], v20 offset0:214 offset1:222
	ds_read2_b32 v[28:29], v20 offset0:247 offset1:255
	v_lshlrev_b64 v[32:33], 11, v[32:33]
	s_waitcnt lgkmcnt(6)
	v_cvt_pk_bf16_f32 v2, v10, v8
	s_waitcnt lgkmcnt(4)
	v_cvt_pk_bf16_f32 v3, v12, v18
	s_waitcnt lgkmcnt(2)
	v_cvt_pk_bf16_f32 v4, v22, v24
	s_waitcnt lgkmcnt(0)
	v_cvt_pk_bf16_f32 v5, v26, v28
	v_lshl_add_u64 v[32:33], v[6:7], 0, v[32:33]
	v_add_u32_e32 v8, 24, v30
	global_store_dwordx4 v[32:33], v[2:5], off nt
	s_nop 1
	v_cvt_pk_bf16_f32 v2, v11, v9
	v_ashrrev_i32_e32 v9, 31, v8
	v_lshlrev_b64 v[8:9], 11, v[8:9]
	v_cvt_pk_bf16_f32 v3, v13, v19
	v_cvt_pk_bf16_f32 v4, v23, v25
	v_cvt_pk_bf16_f32 v5, v27, v29
	v_lshl_add_u64 v[6:7], v[6:7], 0, v[8:9]
	global_store_dwordx4 v[6:7], v[2:5], off nt
	s_waitcnt lgkmcnt(0)
	s_cbranch_scc1 .LBB0_1266
	v_readlane_b32 s50, v255, 24
	v_readlane_b32 s51, v255, 25

; #define LAS __attribute__((address_space(3)))
; __device__ __forceinline__ unsigned pk2(float lo, float hi) { f32x2_t v = {lo, hi}; bf16x2_t b = __builtin_convertvector(v, bf16x2_t); return __builtin_bit_cast(unsigned, b); }
; __device__ __forceinline__ void transpose_item(const float* W, int K, int N, bf16* WT, const float* scale, LAS float* scr, int item, int lane) {
;     const int nblk = N / 32, kb = item / nblk, nb = item % nblk, k0 = 64 * kb, n0 = 32 * nb;
;     {
;         const int q = lane & 7, r = lane >> 3;
;         f32x4 v[8];
; #pragma unroll
;         for (int i = 0; i < 8; ++i) v[i] = *(const f32x4*)(W + (size_t)(k0 + 8 * i + r) * N + n0 + 4 * q);
; #pragma unroll
;         for (int i = 0; i < 8; ++i) { const int kk = 8 * i + r; f32x4 x = v[i]; if (scale) x = x * scale[k0 + kk];
;             scr[kk * 33 + 4 * q + 0] = x[0]; scr[kk * 33 + 4 * q + 1] = x[1]; scr[kk * 33 + 4 * q + 2] = x[2]; scr[kk * 33 + 4 * q + 3] = x[3]; }
;     }
;     asm volatile("s_waitcnt lgkmcnt(0)" ::: "memory");
;     const int c = lane & 7;
; #pragma unroll
;     for (int j = 0; j < 4; ++j) { const int n = (lane >> 3) + 8 * j; const LAS float* s = scr + (8 * c) * 33 + n;
;         v4u o; o.x = pk2(s[0 * 33], s[1 * 33]); o.y = pk2(s[2 * 33], s[3 * 33]); o.z = pk2(s[4 * 33], s[5 * 33]); o.w = pk2(s[6 * 33], s[7 * 33]);
;         *(v4u*)(WT + (size_t)(n0 + n) * K + k0 + 8 * c) = o; }
; __device__ __forceinline__ void convert_weight(const float* W, int K, int N, bf16* WT, const float* scale, LAS unsigned char* lds, int gw, int ngw) {
;     ...
;     for (int it = gw; it < nitems; it += ngw) transpose_item(W, K, N, WT, scale, scr, it, lane);
.LBB0_1270:
	s_sleep 64
	s_mul_hi_i32 s2, s8, 0x2aaaaaab
	s_lshr_b32 s3, s2, 31
	s_ashr_i32 s2, s2, 4
	s_add_i32 s2, s2, s3
	s_lshl_b32 s4, s2, 6
	s_mulk_i32 s2, 0xf400
	s_add_i32 s2, s6, s2
	s_ashr_i32 s3, s2, 31
	s_waitcnt vmcnt(1)
	v_or_b32_e32 v48, s4, v1
	v_lshl_add_u64 v[2:3], s[2:3], 2, v[22:23]
	v_mad_i64_i32 v[4:5], s[10:11], v48, s14, v[2:3]
	global_load_dwordx4 v[36:39], v[4:5], off nt
	v_or_b32_e32 v4, 8, v48
	v_mad_i64_i32 v[4:5], s[10:11], v4, s14, v[2:3]
	global_load_dwordx4 v[40:43], v[4:5], off nt
	v_or_b32_e32 v4, 16, v48
	v_mad_i64_i32 v[4:5], s[10:11], v4, s14, v[2:3]
	global_load_dwordx4 v[44:47], v[4:5], off nt
	v_or_b32_e32 v4, 24, v48
	v_mad_i64_i32 v[4:5], s[10:11], v4, s14, v[2:3]
	global_load_dwordx4 v[18:21], v[4:5], off nt
	v_or_b32_e32 v4, 32, v48
	v_mad_i64_i32 v[4:5], s[10:11], v4, s14, v[2:3]
	global_load_dwordx4 v[14:17], v[4:5], off nt
	v_or_b32_e32 v4, 40, v48
	v_mad_i64_i32 v[4:5], s[10:11], v4, s14, v[2:3]
	global_load_dwordx4 v[10:13], v[4:5], off nt
	v_or_b32_e32 v4, 48, v48
	v_ashrrev_i32_e32 v49, 31, v48
	v_mad_i64_i32 v[4:5], s[10:11], v4, s14, v[2:3]
	global_load_dwordx4 v[6:9], v[4:5], off nt
	v_or_b32_e32 v4, 56, v48
	v_lshl_add_u64 v[48:49], v[48:49], 2, s[12:13]
	global_load_dword v48, v[48:49], off
	v_mad_i64_i32 v[2:3], s[10:11], v4, s14, v[2:3]
	global_load_dwordx4 v[2:5], v[2:3], off nt
	v_add_u32_e32 v35, 0x420, v34
	s_ashr_i32 s5, s4, 31
	s_add_i32 s8, s8, s9
	s_add_i32 s6, s6, s7
	s_cmpk_lt_i32 s8, 0x600
	s_waitcnt vmcnt(1)
	v_pk_mul_f32 v[36:37], v[36:37], v[48:49] op_sel_hi:[1,0]
	v_pk_mul_f32 v[38:39], v[38:39], v[48:49] op_sel_hi:[1,0]
	ds_write2_b32 v34, v36, v37 offset1:1
	ds_write2_b32 v34, v38, v39 offset0:2 offset1:3
	v_or_b32_e32 v36, s4, v26
	v_ashrrev_i32_e32 v37, 31, v36
	v_lshl_add_u64 v[36:37], v[36:37], 2, s[12:13]
	global_load_dword v36, v[36:37], off
	s_waitcnt vmcnt(0)
	v_pk_mul_f32 v[38:39], v[42:43], v[36:37] op_sel_hi:[1,0]
	v_pk_mul_f32 v[36:37], v[40:41], v[36:37] op_sel_hi:[1,0]
	ds_write2_b32 v35, v36, v37 offset1:1
	v_or_b32_e32 v36, s4, v27
	v_ashrrev_i32_e32 v37, 31, v36
	v_lshl_add_u64 v[36:37], v[36:37], 2, s[12:13]
	global_load_dword v36, v[36:37], off
	v_add_u32_e32 v35, 0x428, v34
	ds_write2_b32 v35, v38, v39 offset1:1
	v_add_u32_e32 v35, 0x840, v34
	s_waitcnt vmcnt(0)
	v_pk_mul_f32 v[38:39], v[46:47], v[36:37] op_sel_hi:[1,0]
	v_pk_mul_f32 v[36:37], v[44:45], v[36:37] op_sel_hi:[1,0]
	ds_write2_b32 v35, v36, v37 offset1:1
	v_or_b32_e32 v36, s4, v28
	v_ashrrev_i32_e32 v37, 31, v36
	v_lshl_add_u64 v[36:37], v[36:37], 2, s[12:13]
	global_load_dword v36, v[36:37], off
	v_add_u32_e32 v35, 0x848, v34
	ds_write2_b32 v35, v38, v39 offset1:1
	v_add_u32_e32 v35, 0xc60, v34
	v_add_u32_e32 v38, s2, v1
	v_ashrrev_i32_e32 v39, 31, v38
	v_lshlrev_b64 v[40:41], 11, v[38:39]
	s_waitcnt vmcnt(0)
	v_pk_mul_f32 v[18:19], v[18:19], v[36:37] op_sel_hi:[1,0]
	v_pk_mul_f32 v[20:21], v[20:21], v[36:37] op_sel_hi:[1,0]
	ds_write2_b32 v35, v18, v19 offset1:1
	v_add_u32_e32 v18, 0xc68, v34
	ds_write2_b32 v18, v20, v21 offset1:1
	v_or_b32_e32 v18, s4, v29
	v_ashrrev_i32_e32 v19, 31, v18
	v_lshl_add_u64 v[18:19], v[18:19], 2, s[12:13]
	global_load_dword v18, v[18:19], off
	s_waitcnt vmcnt(0)
	v_pk_mul_f32 v[16:17], v[16:17], v[18:19] op_sel_hi:[1,0]
	v_pk_mul_f32 v[14:15], v[14:15], v[18:19] op_sel_hi:[1,0]
	v_add_u32_e32 v18, 0x1080, v34
	ds_write2_b32 v18, v14, v15 offset1:1
	v_add_u32_e32 v14, 0x1088, v34
	ds_write2_b32 v14, v16, v17 offset1:1
	v_or_b32_e32 v14, s4, v30
	v_ashrrev_i32_e32 v15, 31, v14
	v_lshl_add_u64 v[14:15], v[14:15], 2, s[12:13]
	global_load_dword v14, v[14:15], off
	s_waitcnt vmcnt(0)
	v_pk_mul_f32 v[12:13], v[12:13], v[14:15] op_sel_hi:[1,0]
	v_pk_mul_f32 v[10:11], v[10:11], v[14:15] op_sel_hi:[1,0]
	v_add_u32_e32 v14, 0x14a0, v34
	ds_write2_b32 v14, v10, v11 offset1:1
	v_add_u32_e32 v10, 0x14a8, v34
	ds_write2_b32 v10, v12, v13 offset1:1
	v_or_b32_e32 v10, s4, v31
	v_ashrrev_i32_e32 v11, 31, v10
	v_lshl_add_u64 v[10:11], v[10:11], 2, s[12:13]
	global_load_dword v10, v[10:11], off
	s_waitcnt vmcnt(0)
	v_pk_mul_f32 v[8:9], v[8:9], v[10:11] op_sel_hi:[1,0]
	v_pk_mul_f32 v[6:7], v[6:7], v[10:11] op_sel_hi:[1,0]
	v_add_u32_e32 v10, 0x18c0, v34
	ds_write2_b32 v10, v6, v7 offset1:1
	v_add_u32_e32 v6, 0x18c8, v34
	ds_write2_b32 v6, v8, v9 offset1:1
	v_or_b32_e32 v6, s4, v32
	v_ashrrev_i32_e32 v7, 31, v6
	v_lshl_add_u64 v[6:7], v[6:7], 2, s[12:13]
	global_load_dword v6, v[6:7], off
	s_waitcnt vmcnt(0)
	v_pk_mul_f32 v[4:5], v[4:5], v[6:7] op_sel_hi:[1,0]
	v_pk_mul_f32 v[2:3], v[2:3], v[6:7] op_sel_hi:[1,0]
	v_add_u32_e32 v6, 0x1ce0, v34
	ds_write2_b32 v6, v2, v3 offset1:1
	v_add_u32_e32 v2, 0x1ce8, v34
	ds_write2_b32 v2, v4, v5 offset1:1
	s_waitcnt lgkmcnt(0)
	ds_read2_b32 v[8:9], v33 offset0:33 offset1:41
	ds_read2_b32 v[10:11], v33 offset1:8
	ds_read2_b32 v[12:13], v33 offset0:66 offset1:74
	ds_read2_b32 v[14:15], v33 offset0:99 offset1:107
	ds_read2_b32 v[16:17], v33 offset0:132 offset1:140
	ds_read2_b32 v[18:19], v33 offset0:165 offset1:173
	ds_read2_b32 v[20:21], v33 offset0:198 offset1:206
	ds_read2_b32 v[36:37], v33 offset0:231 offset1:239
	v_lshl_add_u64 v[6:7], s[4:5], 1, v[24:25]
	s_waitcnt lgkmcnt(6)
	v_cvt_pk_bf16_f32 v2, v10, v8
	s_waitcnt lgkmcnt(4)
	v_cvt_pk_bf16_f32 v3, v12, v14
	s_waitcnt lgkmcnt(2)
	v_cvt_pk_bf16_f32 v4, v16, v18
	s_waitcnt lgkmcnt(0)
	v_cvt_pk_bf16_f32 v5, v20, v36
	v_lshl_add_u64 v[40:41], v[6:7], 0, v[40:41]
	v_add_u32_e32 v8, 8, v38
	global_store_dwordx4 v[40:41], v[2:5], off nt
	v_add_u32_e32 v40, 16, v38
	v_ashrrev_i32_e32 v41, 31, v40
	v_cvt_pk_bf16_f32 v2, v11, v9
	v_ashrrev_i32_e32 v9, 31, v8
	v_lshlrev_b64 v[8:9], 11, v[8:9]
	v_cvt_pk_bf16_f32 v3, v13, v15
	v_cvt_pk_bf16_f32 v4, v17, v19
	v_cvt_pk_bf16_f32 v5, v21, v37
	v_lshl_add_u64 v[8:9], v[6:7], 0, v[8:9]
	global_store_dwordx4 v[8:9], v[2:5], off nt
	ds_read2_b32 v[8:9], v33 offset0:49 offset1:57
	ds_read2_b32 v[10:11], v33 offset0:16 offset1:24
	ds_read2_b32 v[12:13], v33 offset0:82 offset1:90
	ds_read2_b32 v[14:15], v33 offset0:115 offset1:123
	ds_read2_b32 v[16:17], v33 offset0:148 offset1:156
	ds_read2_b32 v[18:19], v33 offset0:181 offset1:189
	ds_read2_b32 v[20:21], v33 offset0:214 offset1:222
	ds_read2_b32 v[36:37], v33 offset0:247 offset1:255
	v_lshlrev_b64 v[40:41], 11, v[40:41]
	s_waitcnt lgkmcnt(6)
	v_cvt_pk_bf16_f32 v2, v10, v8
	s_waitcnt lgkmcnt(4)
	v_cvt_pk_bf16_f32 v3, v12, v14
	s_waitcnt lgkmcnt(2)
	v_cvt_pk_bf16_f32 v4, v16, v18
	s_waitcnt lgkmcnt(0)
	v_cvt_pk_bf16_f32 v5, v20, v36
	v_lshl_add_u64 v[40:41], v[6:7], 0, v[40:41]
	v_add_u32_e32 v8, 24, v38
	global_store_dwordx4 v[40:41], v[2:5], off nt
	s_nop 1
	v_cvt_pk_bf16_f32 v2, v11, v9
	v_ashrrev_i32_e32 v9, 31, v8
	v_lshlrev_b64 v[8:9], 11, v[8:9]
	v_cvt_pk_bf16_f32 v3, v13, v15
	v_cvt_pk_bf16_f32 v4, v17, v19
	v_cvt_pk_bf16_f32 v5, v21, v37
	v_lshl_add_u64 v[6:7], v[6:7], 0, v[8:9]
	global_store_dwordx4 v[6:7], v[2:5], off nt
	s_waitcnt lgkmcnt(0)
	s_cbranch_scc1 .LBB0_1270
	v_readlane_b32 s50, v255, 24
	v_readlane_b32 s51, v255, 25

; #define LAS __attribute__((address_space(3)))
; __device__ __forceinline__ unsigned pk2(float lo, float hi) { f32x2_t v = {lo, hi}; bf16x2_t b = __builtin_convertvector(v, bf16x2_t); return __builtin_bit_cast(unsigned, b); }
; __device__ __forceinline__ void transpose_item(const float* W, int K, int N, bf16* WT, const float* scale, LAS float* scr, int item, int lane) {
;     const int nblk = N / 32, kb = item / nblk, nb = item % nblk, k0 = 64 * kb, n0 = 32 * nb;
;     {
;         const int q = lane & 7, r = lane >> 3;
;         f32x4 v[8];
; #pragma unroll
;         for (int i = 0; i < 8; ++i) v[i] = *(const f32x4*)(W + (size_t)(k0 + 8 * i + r) * N + n0 + 4 * q);
; #pragma unroll
;         for (int i = 0; i < 8; ++i) { const int kk = 8 * i + r; f32x4 x = v[i]; if (scale) x = x * scale[k0 + kk];
;             scr[kk * 33 + 4 * q + 0] = x[0]; scr[kk * 33 + 4 * q + 1] = x[1]; scr[kk * 33 + 4 * q + 2] = x[2]; scr[kk * 33 + 4 * q + 3] = x[3]; }
;     }
;     asm volatile("s_waitcnt lgkmcnt(0)" ::: "memory");
;     const int c = lane & 7;
; #pragma unroll
;     for (int j = 0; j < 4; ++j) { const int n = (lane >> 3) + 8 * j; const LAS float* s = scr + (8 * c) * 33 + n;
;         v4u o; o.x = pk2(s[0 * 33], s[1 * 33]); o.y = pk2(s[2 * 33], s[3 * 33]); o.z = pk2(s[4 * 33], s[5 * 33]); o.w = pk2(s[6 * 33], s[7 * 33]);
;         *(v4u*)(WT + (size_t)(n0 + n) * K + k0 + 8 * c) = o; }
; __device__ __forceinline__ void convert_weight(const float* W, int K, int N, bf16* WT, const float* scale, LAS unsigned char* lds, int gw, int ngw) {
;     ...
;     for (int it = gw; it < nitems; it += ngw) transpose_item(W, K, N, WT, scale, scr, it, lane);
.LBB0_1274:
	s_sleep 64
	s_ashr_i32 s0, s6, 31
	s_lshr_b32 s0, s0, 27
	s_add_i32 s0, s6, s0
	s_ashr_i32 s0, s0, 5
	s_lshl_b32 s2, s0, 6
	s_lshl_b32 s0, s0, 10
	s_sub_i32 s0, s4, s0
	s_waitcnt vmcnt(24)
	v_or_b32_e32 v38, s2, v1
	s_ashr_i32 s1, s0, 31
	s_waitcnt vmcnt(22)
	v_ashrrev_i32_e32 v39, 31, v38
	v_or_b32_e32 v6, 8, v38
	v_lshl_add_u64 v[18:19], s[0:1], 2, v[14:15]
	v_lshlrev_b64 v[2:3], 12, v[38:39]
	v_ashrrev_i32_e32 v7, 31, v6
	v_lshl_add_u64 v[2:3], v[18:19], 0, v[2:3]
	v_lshlrev_b64 v[6:7], 12, v[6:7]
	v_or_b32_e32 v10, 16, v38
	global_load_dwordx4 v[2:5], v[2:3], off nt
	v_lshl_add_u64 v[6:7], v[18:19], 0, v[6:7]
	v_ashrrev_i32_e32 v11, 31, v10
	global_load_dwordx4 v[6:9], v[6:7], off nt
	v_lshlrev_b64 v[10:11], 12, v[10:11]
	v_or_b32_e32 v22, 24, v38
	v_lshl_add_u64 v[10:11], v[18:19], 0, v[10:11]
	v_ashrrev_i32_e32 v23, 31, v22
	global_load_dwordx4 v[10:13], v[10:11], off nt
	v_lshlrev_b64 v[22:23], 12, v[22:23]
	v_or_b32_e32 v26, 32, v38
	v_lshl_add_u64 v[22:23], v[18:19], 0, v[22:23]
	v_ashrrev_i32_e32 v27, 31, v26
	global_load_dwordx4 v[22:25], v[22:23], off nt
	v_lshlrev_b64 v[26:27], 12, v[26:27]
	v_or_b32_e32 v30, 40, v38
	v_lshl_add_u64 v[26:27], v[18:19], 0, v[26:27]
	v_ashrrev_i32_e32 v31, 31, v30
	global_load_dwordx4 v[26:29], v[26:27], off nt
	v_lshlrev_b64 v[30:31], 12, v[30:31]
	v_or_b32_e32 v34, 48, v38
	v_lshl_add_u64 v[30:31], v[18:19], 0, v[30:31]
	v_ashrrev_i32_e32 v35, 31, v34
	global_load_dwordx4 v[30:33], v[30:31], off nt
	v_lshlrev_b64 v[34:35], 12, v[34:35]
	v_or_b32_e32 v38, 56, v38
	v_lshl_add_u64 v[34:35], v[18:19], 0, v[34:35]
	v_ashrrev_i32_e32 v39, 31, v38
	global_load_dwordx4 v[34:37], v[34:35], off nt
	v_lshlrev_b64 v[38:39], 12, v[38:39]
	v_lshl_add_u64 v[18:19], v[18:19], 0, v[38:39]
	global_load_dwordx4 v[38:41], v[18:19], off nt
	s_ashr_i32 s3, s2, 31
	s_add_i32 s6, s6, s7
	s_add_i32 s4, s4, s5
	s_cmpk_lt_i32 s6, 0x200
	s_waitcnt vmcnt(7)
	ds_write2_b32 v21, v2, v3 offset1:1
	ds_write2_b32 v21, v4, v5 offset0:2 offset1:3
	v_add_u32_e32 v2, 0x420, v21
	s_waitcnt vmcnt(6)
	ds_write2_b32 v2, v6, v7 offset1:1
	v_add_u32_e32 v2, 0x428, v21
	ds_write2_b32 v2, v8, v9 offset1:1
	v_add_u32_e32 v2, 0x840, v21
	v_lshl_add_u64 v[6:7], s[2:3], 1, v[16:17]
	s_waitcnt vmcnt(5)
	ds_write2_b32 v2, v10, v11 offset1:1
	v_add_u32_e32 v2, 0x848, v21
	ds_write2_b32 v2, v12, v13 offset1:1
	v_add_u32_e32 v2, 0xc60, v21
	s_waitcnt vmcnt(4)
	ds_write2_b32 v2, v22, v23 offset1:1
	v_add_u32_e32 v2, 0xc68, v21
	ds_write2_b32 v2, v24, v25 offset1:1
	v_add_u32_e32 v2, 0x1080, v21
	s_waitcnt vmcnt(3)
	ds_write2_b32 v2, v26, v27 offset1:1
	v_add_u32_e32 v2, 0x1088, v21
	ds_write2_b32 v2, v28, v29 offset1:1
	v_add_u32_e32 v2, 0x14a0, v21
	s_waitcnt vmcnt(2)
	ds_write2_b32 v2, v30, v31 offset1:1
	v_add_u32_e32 v2, 0x14a8, v21
	ds_write2_b32 v2, v32, v33 offset1:1
	v_add_u32_e32 v2, 0x18c0, v21
	v_add_u32_e32 v30, s0, v1
	s_waitcnt vmcnt(1)
	ds_write2_b32 v2, v34, v35 offset1:1
	v_add_u32_e32 v2, 0x18c8, v21
	ds_write2_b32 v2, v36, v37 offset1:1
	v_add_u32_e32 v2, 0x1ce0, v21
	s_waitcnt vmcnt(0)
	ds_write2_b32 v2, v38, v39 offset1:1
	v_add_u32_e32 v2, 0x1ce8, v21
	ds_write2_b32 v2, v40, v41 offset1:1
	s_waitcnt lgkmcnt(0)
	ds_read2_b32 v[8:9], v20 offset0:33 offset1:41
	ds_read2_b32 v[10:11], v20 offset1:8
	ds_read2_b32 v[12:13], v20 offset0:66 offset1:74
	ds_read2_b32 v[18:19], v20 offset0:99 offset1:107
	ds_read2_b32 v[22:23], v20 offset0:132 offset1:140
	ds_read2_b32 v[24:25], v20 offset0:165 offset1:173
	ds_read2_b32 v[26:27], v20 offset0:198 offset1:206
	ds_read2_b32 v[28:29], v20 offset0:231 offset1:239
	v_ashrrev_i32_e32 v31, 31, v30
	v_lshlrev_b64 v[32:33], 11, v[30:31]
	s_waitcnt lgkmcnt(6)
	v_cvt_pk_bf16_f32 v2, v10, v8
	s_waitcnt lgkmcnt(4)
	v_cvt_pk_bf16_f32 v3, v12, v18
	s_waitcnt lgkmcnt(2)
	v_cvt_pk_bf16_f32 v4, v22, v24
	s_waitcnt lgkmcnt(0)
	v_cvt_pk_bf16_f32 v5, v26, v28
	v_lshl_add_u64 v[32:33], v[6:7], 0, v[32:33]
	v_add_u32_e32 v8, 8, v30
	global_store_dwordx4 v[32:33], v[2:5], off nt
	v_add_u32_e32 v32, 16, v30
	v_ashrrev_i32_e32 v33, 31, v32
	v_cvt_pk_bf16_f32 v2, v11, v9
	v_ashrrev_i32_e32 v9, 31, v8
	v_lshlrev_b64 v[8:9], 11, v[8:9]
	v_cvt_pk_bf16_f32 v3, v13, v19
	v_cvt_pk_bf16_f32 v4, v23, v25
	v_cvt_pk_bf16_f32 v5, v27, v29
	v_lshl_add_u64 v[8:9], v[6:7], 0, v[8:9]
	global_store_dwordx4 v[8:9], v[2:5], off nt
	ds_read2_b32 v[8:9], v20 offset0:49 offset1:57
	ds_read2_b32 v[10:11], v20 offset0:16 offset1:24
	ds_read2_b32 v[12:13], v20 offset0:82 offset1:90
	ds_read2_b32 v[18:19], v20 offset0:115 offset1:123
	ds_read2_b32 v[22:23], v20 offset0:148 offset1:156
	ds_read2_b32 v[24:25], v20 offset0:181 offset1:189
	ds_read2_b32 v[26:27], v20 offset0:214 offset1:222
	ds_read2_b32 v[28:29], v20 offset0:247 offset1:255
	v_lshlrev_b64 v[32:33], 11, v[32:33]
	s_waitcnt lgkmcnt(6)
	v_cvt_pk_bf16_f32 v2, v10, v8
	s_waitcnt lgkmcnt(4)
	v_cvt_pk_bf16_f32 v3, v12, v18
	s_waitcnt lgkmcnt(2)
	v_cvt_pk_bf16_f32 v4, v22, v24
	s_waitcnt lgkmcnt(0)
	v_cvt_pk_bf16_f32 v5, v26, v28
	v_lshl_add_u64 v[32:33], v[6:7], 0, v[32:33]
	v_add_u32_e32 v8, 24, v30
	global_store_dwordx4 v[32:33], v[2:5], off nt
	s_nop 1
	v_cvt_pk_bf16_f32 v2, v11, v9
	v_ashrrev_i32_e32 v9, 31, v8
	v_lshlrev_b64 v[8:9], 11, v[8:9]
	v_cvt_pk_bf16_f32 v3, v13, v19
	v_cvt_pk_bf16_f32 v4, v23, v25
	v_cvt_pk_bf16_f32 v5, v27, v29
	v_lshl_add_u64 v[6:7], v[6:7], 0, v[8:9]
	global_store_dwordx4 v[6:7], v[2:5], off nt
	s_waitcnt lgkmcnt(0)
	s_cbranch_scc1 .LBB0_1274
	v_readlane_b32 s50, v255, 24
	v_readlane_b32 s51, v255, 25

; __device__ __forceinline__ void transpose_item(const float* W, int K, int N, bf16* WT, const float* scale, LAS float* scr, int item, int lane) {
;     const int nblk = N / 32, kb = item / nblk, nb = item % nblk, k0 = 64 * kb, n0 = 32 * nb;
;     {
;         const int q = lane & 7, r = lane >> 3;
;         f32x4 v[8];
; #pragma unroll
;         for (int i = 0; i < 8; ++i) v[i] = *(const f32x4*)(W + (size_t)(k0 + 8 * i + r) * N + n0 + 4 * q);
; #pragma unroll
;         for (int i = 0; i < 8; ++i) { const int kk = 8 * i + r; f32x4 x = v[i]; if (scale) x = x * scale[k0 + kk];
;             scr[kk * 33 + 4 * q + 0] = x[0]; scr[kk * 33 + 4 * q + 1] = x[1]; scr[kk * 33 + 4 * q + 2] = x[2]; scr[kk * 33 + 4 * q + 3] = x[3]; }
.LBB0_1278:
	s_sleep 64
	s_ashr_i32 s0, s6, 31
	s_lshr_b32 s0, s0, 25
	s_add_i32 s0, s6, s0
	s_ashr_i32 s0, s0, 7
	s_lshl_b32 s2, s0, 6
	s_lshl_b32 s0, s0, 12
	s_sub_i32 s0, s4, s0
	s_waitcnt vmcnt(1)
	v_or_b32_e32 v48, s2, v1
	s_ashr_i32 s1, s0, 31
	v_ashrrev_i32_e32 v49, 31, v48
	v_lshl_add_u64 v[2:3], s[0:1], 2, v[26:27]
	v_lshlrev_b64 v[4:5], 14, v[48:49]
	v_lshl_add_u64 v[4:5], v[2:3], 0, v[4:5]
	global_load_dwordx4 v[30:33], v[4:5], off nt
	v_or_b32_e32 v4, 8, v48
	v_ashrrev_i32_e32 v5, 31, v4
	v_lshlrev_b64 v[4:5], 14, v[4:5]
	v_lshl_add_u64 v[4:5], v[2:3], 0, v[4:5]
	global_load_dwordx4 v[44:47], v[4:5], off nt
	v_or_b32_e32 v4, 16, v48
	v_ashrrev_i32_e32 v5, 31, v4
	v_lshlrev_b64 v[4:5], 14, v[4:5]
	v_lshl_add_u64 v[4:5], v[2:3], 0, v[4:5]
	global_load_dwordx4 v[22:25], v[4:5], off nt
	v_or_b32_e32 v4, 24, v48
	v_ashrrev_i32_e32 v5, 31, v4
	v_lshlrev_b64 v[4:5], 14, v[4:5]
	v_lshl_add_u64 v[4:5], v[2:3], 0, v[4:5]
	global_load_dwordx4 v[18:21], v[4:5], off nt
	v_or_b32_e32 v4, 32, v48
	v_ashrrev_i32_e32 v5, 31, v4
	v_lshlrev_b64 v[4:5], 14, v[4:5]
	v_lshl_add_u64 v[4:5], v[2:3], 0, v[4:5]
	global_load_dwordx4 v[14:17], v[4:5], off nt
	v_or_b32_e32 v4, 40, v48
	v_ashrrev_i32_e32 v5, 31, v4
	v_lshlrev_b64 v[4:5], 14, v[4:5]
	v_lshl_add_u64 v[4:5], v[2:3], 0, v[4:5]
	global_load_dwordx4 v[10:13], v[4:5], off nt
	v_or_b32_e32 v4, 48, v48
	v_ashrrev_i32_e32 v5, 31, v4
	v_lshlrev_b64 v[4:5], 14, v[4:5]
	v_lshl_add_u64 v[4:5], v[2:3], 0, v[4:5]
	global_load_dwordx4 v[6:9], v[4:5], off nt
	v_or_b32_e32 v4, 56, v48
	v_lshl_add_u64 v[48:49], v[48:49], 2, s[8:9]
	global_load_dword v48, v[48:49], off
	v_ashrrev_i32_e32 v5, 31, v4
	v_lshlrev_b64 v[4:5], 14, v[4:5]
	v_lshl_add_u64 v[2:3], v[2:3], 0, v[4:5]
	global_load_dwordx4 v[2:5], v[2:3], off nt
	v_add_u32_e32 v43, 0x420, v42
	s_ashr_i32 s3, s2, 31
	s_add_i32 s6, s6, s7
	s_add_i32 s4, s4, s5
	s_cmpk_lt_i32 s6, 0x800
	s_waitcnt vmcnt(1)
	v_pk_mul_f32 v[30:31], v[30:31], v[48:49] op_sel_hi:[1,0]
	v_pk_mul_f32 v[32:33], v[32:33], v[48:49] op_sel_hi:[1,0]
	ds_write2_b32 v42, v30, v31 offset1:1
	ds_write2_b32 v42, v32, v33 offset0:2 offset1:3
	v_or_b32_e32 v30, s2, v34
	v_ashrrev_i32_e32 v31, 31, v30
	v_lshl_add_u64 v[30:31], v[30:31], 2, s[8:9]
	global_load_dword v32, v[30:31], off
	s_waitcnt vmcnt(0)
	v_pk_mul_f32 v[30:31], v[46:47], v[32:33] op_sel_hi:[1,0]
	v_pk_mul_f32 v[32:33], v[44:45], v[32:33] op_sel_hi:[1,0]
	ds_write2_b32 v43, v32, v33 offset1:1
	v_add_u32_e32 v32, 0x428, v42
	ds_write2_b32 v32, v30, v31 offset1:1
	v_or_b32_e32 v30, s2, v35
	v_ashrrev_i32_e32 v31, 31, v30
	v_lshl_add_u64 v[30:31], v[30:31], 2, s[8:9]
	global_load_dword v30, v[30:31], off
	s_waitcnt vmcnt(0)
	v_pk_mul_f32 v[24:25], v[24:25], v[30:31] op_sel_hi:[1,0]
	v_pk_mul_f32 v[22:23], v[22:23], v[30:31] op_sel_hi:[1,0]
	v_add_u32_e32 v30, 0x840, v42
	ds_write2_b32 v30, v22, v23 offset1:1
	v_add_u32_e32 v22, 0x848, v42
	ds_write2_b32 v22, v24, v25 offset1:1
	v_or_b32_e32 v22, s2, v36
	v_ashrrev_i32_e32 v23, 31, v22
	v_lshl_add_u64 v[22:23], v[22:23], 2, s[8:9]
	global_load_dword v22, v[22:23], off
	v_add_u32_e32 v24, s0, v1
	v_ashrrev_i32_e32 v25, 31, v24
	v_lshlrev_b64 v[30:31], 11, v[24:25]
	s_waitcnt vmcnt(0)
	v_pk_mul_f32 v[20:21], v[20:21], v[22:23] op_sel_hi:[1,0]
	v_pk_mul_f32 v[18:19], v[18:19], v[22:23] op_sel_hi:[1,0]
	v_add_u32_e32 v22, 0xc60, v42
	ds_write2_b32 v22, v18, v19 offset1:1
	v_add_u32_e32 v18, 0xc68, v42
	ds_write2_b32 v18, v20, v21 offset1:1
	v_or_b32_e32 v18, s2, v37
	v_ashrrev_i32_e32 v19, 31, v18
	v_lshl_add_u64 v[18:19], v[18:19], 2, s[8:9]
	global_load_dword v18, v[18:19], off
	s_waitcnt vmcnt(0)
; #define LAS __attribute__((address_space(3)))
; __device__ __forceinline__ unsigned pk2(float lo, float hi) { f32x2_t v = {lo, hi}; bf16x2_t b = __builtin_convertvector(v, bf16x2_t); return __builtin_bit_cast(unsigned, b); }
; __device__ __forceinline__ void transpose_item(const float* W, int K, int N, bf16* WT, const float* scale, LAS float* scr, int item, int lane) {
;     ...
;         for (int i = 0; i < 8; ++i) { const int kk = 8 * i + r; f32x4 x = v[i]; if (scale) x = x * scale[k0 + kk];
;             scr[kk * 33 + 4 * q + 0] = x[0]; scr[kk * 33 + 4 * q + 1] = x[1]; scr[kk * 33 + 4 * q + 2] = x[2]; scr[kk * 33 + 4 * q + 3] = x[3]; }
;     }
;     asm volatile("s_waitcnt lgkmcnt(0)" ::: "memory");
;     const int c = lane & 7;
; #pragma unroll
;     for (int j = 0; j < 4; ++j) { const int n = (lane >> 3) + 8 * j; const LAS float* s = scr + (8 * c) * 33 + n;
;         v4u o; o.x = pk2(s[0 * 33], s[1 * 33]); o.y = pk2(s[2 * 33], s[3 * 33]); o.z = pk2(s[4 * 33], s[5 * 33]); o.w = pk2(s[6 * 33], s[7 * 33]);
;         *(v4u*)(WT + (size_t)(n0 + n) * K + k0 + 8 * c) = o; }
	v_pk_mul_f32 v[16:17], v[16:17], v[18:19] op_sel_hi:[1,0]
	v_pk_mul_f32 v[14:15], v[14:15], v[18:19] op_sel_hi:[1,0]
	v_add_u32_e32 v18, 0x1080, v42
	ds_write2_b32 v18, v14, v15 offset1:1
	v_add_u32_e32 v14, 0x1088, v42
	ds_write2_b32 v14, v16, v17 offset1:1
	v_or_b32_e32 v14, s2, v38
	v_ashrrev_i32_e32 v15, 31, v14
	v_lshl_add_u64 v[14:15], v[14:15], 2, s[8:9]
	global_load_dword v14, v[14:15], off
	s_waitcnt vmcnt(0)
	v_pk_mul_f32 v[12:13], v[12:13], v[14:15] op_sel_hi:[1,0]
	v_pk_mul_f32 v[10:11], v[10:11], v[14:15] op_sel_hi:[1,0]
	v_add_u32_e32 v14, 0x14a0, v42
	ds_write2_b32 v14, v10, v11 offset1:1
	v_add_u32_e32 v10, 0x14a8, v42
	ds_write2_b32 v10, v12, v13 offset1:1
	v_or_b32_e32 v10, s2, v39
	v_ashrrev_i32_e32 v11, 31, v10
	v_lshl_add_u64 v[10:11], v[10:11], 2, s[8:9]
	global_load_dword v10, v[10:11], off
	s_waitcnt vmcnt(0)
	v_pk_mul_f32 v[8:9], v[8:9], v[10:11] op_sel_hi:[1,0]
	v_pk_mul_f32 v[6:7], v[6:7], v[10:11] op_sel_hi:[1,0]
	v_add_u32_e32 v10, 0x18c0, v42
	ds_write2_b32 v10, v6, v7 offset1:1
	v_add_u32_e32 v6, 0x18c8, v42
	ds_write2_b32 v6, v8, v9 offset1:1
	v_or_b32_e32 v6, s2, v40
	v_ashrrev_i32_e32 v7, 31, v6
	v_lshl_add_u64 v[6:7], v[6:7], 2, s[8:9]
	global_load_dword v6, v[6:7], off
	s_waitcnt vmcnt(0)
	v_pk_mul_f32 v[4:5], v[4:5], v[6:7] op_sel_hi:[1,0]
	v_pk_mul_f32 v[2:3], v[2:3], v[6:7] op_sel_hi:[1,0]
	v_add_u32_e32 v6, 0x1ce0, v42
	ds_write2_b32 v6, v2, v3 offset1:1
	v_add_u32_e32 v2, 0x1ce8, v42
	ds_write2_b32 v2, v4, v5 offset1:1
	s_waitcnt lgkmcnt(0)
	ds_read2_b32 v[8:9], v41 offset0:33 offset1:41
	ds_read2_b32 v[10:11], v41 offset1:8
	ds_read2_b32 v[12:13], v41 offset0:66 offset1:74
	ds_read2_b32 v[14:15], v41 offset0:99 offset1:107
	ds_read2_b32 v[16:17], v41 offset0:132 offset1:140
	ds_read2_b32 v[18:19], v41 offset0:165 offset1:173
	ds_read2_b32 v[20:21], v41 offset0:198 offset1:206
	ds_read2_b32 v[22:23], v41 offset0:231 offset1:239
	v_lshl_add_u64 v[6:7], s[2:3], 1, v[28:29]
	s_waitcnt lgkmcnt(6)
	v_cvt_pk_bf16_f32 v2, v10, v8
	s_waitcnt lgkmcnt(4)
	v_cvt_pk_bf16_f32 v3, v12, v14
	s_waitcnt lgkmcnt(2)
	v_cvt_pk_bf16_f32 v4, v16, v18
	s_waitcnt lgkmcnt(0)
	v_cvt_pk_bf16_f32 v5, v20, v22
	v_lshl_add_u64 v[30:31], v[6:7], 0, v[30:31]
	v_add_u32_e32 v8, 8, v24
	global_store_dwordx4 v[30:31], v[2:5], off nt
	v_add_u32_e32 v30, 16, v24
	v_ashrrev_i32_e32 v31, 31, v30
	v_cvt_pk_bf16_f32 v2, v11, v9
	v_ashrrev_i32_e32 v9, 31, v8
	v_lshlrev_b64 v[8:9], 11, v[8:9]
	v_cvt_pk_bf16_f32 v3, v13, v15
	v_cvt_pk_bf16_f32 v4, v17, v19
	v_cvt_pk_bf16_f32 v5, v21, v23
	v_lshl_add_u64 v[8:9], v[6:7], 0, v[8:9]
	global_store_dwordx4 v[8:9], v[2:5], off nt
	ds_read2_b32 v[8:9], v41 offset0:49 offset1:57
	ds_read2_b32 v[10:11], v41 offset0:16 offset1:24
	ds_read2_b32 v[12:13], v41 offset0:82 offset1:90
	ds_read2_b32 v[14:15], v41 offset0:115 offset1:123
	ds_read2_b32 v[16:17], v41 offset0:148 offset1:156
	ds_read2_b32 v[18:19], v41 offset0:181 offset1:189
	ds_read2_b32 v[20:21], v41 offset0:214 offset1:222
	ds_read2_b32 v[22:23], v41 offset0:247 offset1:255
	v_lshlrev_b64 v[30:31], 11, v[30:31]
	s_waitcnt lgkmcnt(6)
	v_cvt_pk_bf16_f32 v2, v10, v8
	s_waitcnt lgkmcnt(4)
	v_cvt_pk_bf16_f32 v3, v12, v14
	s_waitcnt lgkmcnt(2)
	v_cvt_pk_bf16_f32 v4, v16, v18
	s_waitcnt lgkmcnt(0)
	v_cvt_pk_bf16_f32 v5, v20, v22
	v_lshl_add_u64 v[30:31], v[6:7], 0, v[30:31]
	v_add_u32_e32 v8, 24, v24
	global_store_dwordx4 v[30:31], v[2:5], off nt
	s_nop 1
	v_cvt_pk_bf16_f32 v2, v11, v9
	v_ashrrev_i32_e32 v9, 31, v8
	v_lshlrev_b64 v[8:9], 11, v[8:9]
	v_cvt_pk_bf16_f32 v3, v13, v15
	v_cvt_pk_bf16_f32 v4, v17, v19
	v_cvt_pk_bf16_f32 v5, v21, v23
	v_lshl_add_u64 v[6:7], v[6:7], 0, v[8:9]
	global_store_dwordx4 v[6:7], v[2:5], off nt
	s_waitcnt lgkmcnt(0)
	s_cbranch_scc1 .LBB0_1278
